# GEMM row-scale table build: the 24 partial-sum loads of all 6 row blocks issued together, then the 6 rsqrt chains (same arithmetic order)
# speedup vs baseline: 1.0082x; 1.0012x over previous
; #define TIDX tid_opaque()
; __device__ __forceinline__ void run_gemm(unsigned char* smem, const GDesc& d) {
;     ...
;         const float* part = (const float*)d.q3; float* rtab = (float*)(smem + RT_OFF); int* pmtab = (int*)(smem + RT_OFF + 12 * 1024); const int tid = TIDX;
;         if (tid < 16) { pg8::Unit u; pmtab[tid] = S.next(tid, u) ? u.pm : -1; }
;         __syncthreads();
; #pragma unroll
;         for (int k = 0; k < 6; ++k) { const int idx = tid + 512 * k, i = idx >> 8, row = idx & 255; const int pm = (i < 12) ? pmtab[i] : -1;
;             if (pm >= 0) { const f32x4* pp = (const f32x4*)(part + (size_t)(pm * BM + row) * 16); const f32x4 a = pp[0], b = pp[1], c = pp[2], e4 = pp[3];
;                 const float ss = ((a[0] + a[1]) + (a[2] + a[3])) + ((b[0] + b[1]) + (b[2] + b[3])) + ((c[0] + c[1]) + (c[2] + c[3])) + ((e4[0] + e4[1]) + (e4[2] + e4[3]));
;                 rtab[idx] = 1.0f / sqrtf(ss * (1.0f / DM) + 1e-6f); } }
;         __syncthreads();
.LBB0_417:
	s_or_b64 exec, exec, s[0:1]
	v_ashrrev_i32_e32 v0, 8, v2
	v_cmp_gt_i32_e32 vcc, 12, v0
	v_mov_b32_e32 v1, -1
	s_waitcnt lgkmcnt(0)
	s_barrier
	s_waitcnt vmcnt(0)
	v_ashrrev_i32_e32 v1, 8, v2
	v_lshl_add_u32 v23, v1, 2, 0
	v_add_u32_e32 v23, 0x23000, v23
	v_lshl_add_u32 v22, v2, 2, 0
	v_add_u32_e32 v22, 0x20000, v22
	v_and_b32_e32 v0, 0xff, v2
	ds_read_b32 v120, v23
	ds_read_b32 v121, v23 offset:8
	ds_read_b32 v122, v23 offset:16
	ds_read_b32 v123, v23 offset:24
	ds_read_b32 v124, v23 offset:32
	ds_read_b32 v125, v23 offset:40
	s_waitcnt lgkmcnt(0)
	v_max_i32_e32 v3, 0, v120
	v_lshl_or_b32 v184, v3, 8, v0
	v_lshlrev_b64 v[4:5], 6, v[184:185]
	v_lshl_add_u64 v[6:7], s[20:21], 0, v[4:5]
	global_load_dwordx4 v[24:27], v[6:7], off
	global_load_dwordx4 v[28:31], v[6:7], off offset:16
	global_load_dwordx4 v[32:35], v[6:7], off offset:32
	global_load_dwordx4 v[36:39], v[6:7], off offset:48
	v_max_i32_e32 v3, 0, v121
	v_lshl_or_b32 v184, v3, 8, v0
	v_lshlrev_b64 v[4:5], 6, v[184:185]
	v_lshl_add_u64 v[6:7], s[20:21], 0, v[4:5]
	global_load_dwordx4 v[40:43], v[6:7], off
	global_load_dwordx4 v[44:47], v[6:7], off offset:16
	global_load_dwordx4 v[48:51], v[6:7], off offset:32
	global_load_dwordx4 v[52:55], v[6:7], off offset:48
	v_max_i32_e32 v3, 0, v122
	v_lshl_or_b32 v184, v3, 8, v0
	v_lshlrev_b64 v[4:5], 6, v[184:185]
	v_lshl_add_u64 v[6:7], s[20:21], 0, v[4:5]
	global_load_dwordx4 v[56:59], v[6:7], off
	global_load_dwordx4 v[60:63], v[6:7], off offset:16
	global_load_dwordx4 v[64:67], v[6:7], off offset:32
	global_load_dwordx4 v[68:71], v[6:7], off offset:48
	v_max_i32_e32 v3, 0, v123
	v_lshl_or_b32 v184, v3, 8, v0
	v_lshlrev_b64 v[4:5], 6, v[184:185]
	v_lshl_add_u64 v[6:7], s[20:21], 0, v[4:5]
	global_load_dwordx4 v[72:75], v[6:7], off
	global_load_dwordx4 v[76:79], v[6:7], off offset:16
	global_load_dwordx4 v[80:83], v[6:7], off offset:32
	global_load_dwordx4 v[84:87], v[6:7], off offset:48
	v_max_i32_e32 v3, 0, v124
	v_lshl_or_b32 v184, v3, 8, v0
	v_lshlrev_b64 v[4:5], 6, v[184:185]
	v_lshl_add_u64 v[6:7], s[20:21], 0, v[4:5]
	global_load_dwordx4 v[88:91], v[6:7], off
	global_load_dwordx4 v[92:95], v[6:7], off offset:16
	global_load_dwordx4 v[96:99], v[6:7], off offset:32
	global_load_dwordx4 v[100:103], v[6:7], off offset:48
	v_max_i32_e32 v3, 0, v125
	v_lshl_or_b32 v184, v3, 8, v0
	v_lshlrev_b64 v[4:5], 6, v[184:185]
	v_lshl_add_u64 v[6:7], s[20:21], 0, v[4:5]
	global_load_dwordx4 v[104:107], v[6:7], off
	global_load_dwordx4 v[108:111], v[6:7], off offset:16
	global_load_dwordx4 v[112:115], v[6:7], off offset:32
	global_load_dwordx4 v[116:119], v[6:7], off offset:48
	s_waitcnt vmcnt(20)
	v_add_f32_e32 v4, v25, v24
	v_add_f32_e32 v5, v26, v27
	v_add_f32_e32 v6, v29, v28
	v_add_f32_e32 v7, v30, v31
	v_add_f32_e32 v4, v4, v5
	v_add_f32_e32 v6, v6, v7
	v_add_f32_e32 v10, v32, v33
	v_add_f32_e32 v12, v34, v35
	v_add_f32_e32 v8, v10, v12
	v_add_f32_e32 v5, v36, v37
	v_add_f32_e32 v9, v38, v39
	v_add_f32_e32 v4, v4, v6
	v_add_f32_e32 v5, v5, v9
	v_add_f32_e32 v4, v4, v8
	v_add_f32_e32 v1, v4, v5
	v_fmamk_f32 v1, v1, 0x3a800000, v235
	s_mov_b32 s0, 0xf800000
	v_mul_f32_e32 v3, 0x4f800000, v1
	v_cmp_gt_f32_e32 vcc, s0, v1
	s_nop 1
	v_cndmask_b32_e32 v1, v1, v3, vcc
	v_sqrt_f32_e32 v3, v1
	s_nop 0
	v_add_u32_e32 v4, -1, v3
	v_add_u32_e32 v5, 1, v3
	v_fma_f32 v6, -v4, v3, v1
	v_fma_f32 v7, -v5, v3, v1
	v_cmp_ge_f32_e64 s[0:1], 0, v6
	s_nop 1
	v_cndmask_b32_e64 v3, v3, v4, s[0:1]
	v_cmp_lt_f32_e64 s[0:1], 0, v7
	s_nop 1
	v_cndmask_b32_e64 v3, v3, v5, s[0:1]
	v_mul_f32_e32 v4, 0x37800000, v3
	v_cndmask_b32_e32 v3, v3, v4, vcc
	v_cmp_class_f32_e32 vcc, v1, v236
	s_nop 1
	v_cndmask_b32_e32 v1, v3, v1, vcc
	v_div_scale_f32 v3, s[0:1], v1, v1, 1.0
	v_rcp_f32_e32 v4, v3
	v_div_scale_f32 v6, vcc, 1.0, v1, 1.0
	v_fma_f32 v7, -v3, v4, 1.0
	v_fmac_f32_e32 v4, v7, v4
	v_mul_f32_e32 v7, v6, v4
	v_fma_f32 v8, -v3, v7, v6
	v_fmac_f32_e32 v7, v8, v4
	v_fma_f32 v3, -v3, v7, v6
	v_div_fmas_f32 v3, v3, v4, v7
	v_div_fixup_f32 v1, v3, v1, 1.0
	v_cmp_lt_i32_e32 vcc, -1, v120
	s_and_saveexec_b64 s[6:7], vcc
	ds_write_b32 v22, v1
	s_mov_b64 exec, s[6:7]
	s_waitcnt vmcnt(16)
	v_add_f32_e32 v4, v41, v40
	v_add_f32_e32 v5, v42, v43
	v_add_f32_e32 v6, v45, v44
	v_add_f32_e32 v7, v46, v47
	v_add_f32_e32 v4, v4, v5
	v_add_f32_e32 v6, v6, v7
	v_add_f32_e32 v10, v48, v49
	v_add_f32_e32 v12, v50, v51
	v_add_f32_e32 v8, v10, v12
	v_add_f32_e32 v5, v52, v53
	v_add_f32_e32 v9, v54, v55
	v_add_f32_e32 v4, v4, v6
	v_add_f32_e32 v5, v5, v9
	v_add_f32_e32 v4, v4, v8
	v_add_f32_e32 v1, v4, v5
	v_fmamk_f32 v1, v1, 0x3a800000, v235
	s_mov_b32 s0, 0xf800000
	v_mul_f32_e32 v3, 0x4f800000, v1
	v_cmp_gt_f32_e32 vcc, s0, v1
	s_nop 1
	v_cndmask_b32_e32 v1, v1, v3, vcc
	v_sqrt_f32_e32 v3, v1
	s_nop 0
	v_add_u32_e32 v4, -1, v3
	v_add_u32_e32 v5, 1, v3
	v_fma_f32 v6, -v4, v3, v1
	v_fma_f32 v7, -v5, v3, v1
	v_cmp_ge_f32_e64 s[0:1], 0, v6
	s_nop 1
	v_cndmask_b32_e64 v3, v3, v4, s[0:1]
	v_cmp_lt_f32_e64 s[0:1], 0, v7
	s_nop 1
	v_cndmask_b32_e64 v3, v3, v5, s[0:1]
	v_mul_f32_e32 v4, 0x37800000, v3
	v_cndmask_b32_e32 v3, v3, v4, vcc
	v_cmp_class_f32_e32 vcc, v1, v236
	s_nop 1
	v_cndmask_b32_e32 v1, v3, v1, vcc
	v_div_scale_f32 v3, s[0:1], v1, v1, 1.0
	v_rcp_f32_e32 v4, v3
	v_div_scale_f32 v6, vcc, 1.0, v1, 1.0
	v_fma_f32 v7, -v3, v4, 1.0
	v_fmac_f32_e32 v4, v7, v4
	v_mul_f32_e32 v7, v6, v4
	v_fma_f32 v8, -v3, v7, v6
	v_fmac_f32_e32 v7, v8, v4
	v_fma_f32 v3, -v3, v7, v6
	v_div_fmas_f32 v3, v3, v4, v7
	v_div_fixup_f32 v1, v3, v1, 1.0
	v_cmp_lt_i32_e32 vcc, -1, v121
	s_and_saveexec_b64 s[6:7], vcc
	ds_write_b32 v22, v1 offset:2048
	s_mov_b64 exec, s[6:7]
	s_waitcnt vmcnt(12)
; __device__ __forceinline__ void run_gemm(unsigned char* smem, const GDesc& d) {
;     ...
;         for (int k = 0; k < 6; ++k) { const int idx = tid + 512 * k, i = idx >> 8, row = idx & 255; const int pm = (i < 12) ? pmtab[i] : -1;
;             if (pm >= 0) { const f32x4* pp = (const f32x4*)(part + (size_t)(pm * BM + row) * 16); const f32x4 a = pp[0], b = pp[1], c = pp[2], e4 = pp[3];
;                 const float ss = ((a[0] + a[1]) + (a[2] + a[3])) + ((b[0] + b[1]) + (b[2] + b[3])) + ((c[0] + c[1]) + (c[2] + c[3])) + ((e4[0] + e4[1]) + (e4[2] + e4[3]));
;                 rtab[idx] = 1.0f / sqrtf(ss * (1.0f / DM) + 1e-6f); } }
	v_add_f32_e32 v4, v57, v56
	v_add_f32_e32 v5, v58, v59
	v_add_f32_e32 v6, v61, v60
	v_add_f32_e32 v7, v62, v63
	v_add_f32_e32 v4, v4, v5
	v_add_f32_e32 v6, v6, v7
	v_add_f32_e32 v10, v64, v65
	v_add_f32_e32 v12, v66, v67
	v_add_f32_e32 v8, v10, v12
	v_add_f32_e32 v5, v68, v69
	v_add_f32_e32 v9, v70, v71
	v_add_f32_e32 v4, v4, v6
	v_add_f32_e32 v5, v5, v9
	v_add_f32_e32 v4, v4, v8
	v_add_f32_e32 v1, v4, v5
	v_fmamk_f32 v1, v1, 0x3a800000, v235
	s_mov_b32 s0, 0xf800000
	v_mul_f32_e32 v3, 0x4f800000, v1
	v_cmp_gt_f32_e32 vcc, s0, v1
	s_nop 1
	v_cndmask_b32_e32 v1, v1, v3, vcc
	v_sqrt_f32_e32 v3, v1
	s_nop 0
	v_add_u32_e32 v4, -1, v3
	v_add_u32_e32 v5, 1, v3
	v_fma_f32 v6, -v4, v3, v1
	v_fma_f32 v7, -v5, v3, v1
	v_cmp_ge_f32_e64 s[0:1], 0, v6
	s_nop 1
	v_cndmask_b32_e64 v3, v3, v4, s[0:1]
	v_cmp_lt_f32_e64 s[0:1], 0, v7
	s_nop 1
	v_cndmask_b32_e64 v3, v3, v5, s[0:1]
	v_mul_f32_e32 v4, 0x37800000, v3
	v_cndmask_b32_e32 v3, v3, v4, vcc
	v_cmp_class_f32_e32 vcc, v1, v236
	s_nop 1
	v_cndmask_b32_e32 v1, v3, v1, vcc
	v_div_scale_f32 v3, s[0:1], v1, v1, 1.0
	v_rcp_f32_e32 v4, v3
	v_div_scale_f32 v6, vcc, 1.0, v1, 1.0
	v_fma_f32 v7, -v3, v4, 1.0
	v_fmac_f32_e32 v4, v7, v4
	v_mul_f32_e32 v7, v6, v4
	v_fma_f32 v8, -v3, v7, v6
	v_fmac_f32_e32 v7, v8, v4
	v_fma_f32 v3, -v3, v7, v6
	v_div_fmas_f32 v3, v3, v4, v7
	v_div_fixup_f32 v1, v3, v1, 1.0
	v_cmp_lt_i32_e32 vcc, -1, v122
	s_and_saveexec_b64 s[6:7], vcc
	ds_write_b32 v22, v1 offset:4096
	s_mov_b64 exec, s[6:7]
	s_waitcnt vmcnt(8)
	v_add_f32_e32 v4, v73, v72
	v_add_f32_e32 v5, v74, v75
	v_add_f32_e32 v6, v77, v76
	v_add_f32_e32 v7, v78, v79
	v_add_f32_e32 v4, v4, v5
	v_add_f32_e32 v6, v6, v7
	v_add_f32_e32 v10, v80, v81
	v_add_f32_e32 v12, v82, v83
	v_add_f32_e32 v8, v10, v12
	v_add_f32_e32 v5, v84, v85
	v_add_f32_e32 v9, v86, v87
	v_add_f32_e32 v4, v4, v6
	v_add_f32_e32 v5, v5, v9
	v_add_f32_e32 v4, v4, v8
	v_add_f32_e32 v1, v4, v5
	v_fmamk_f32 v1, v1, 0x3a800000, v235
	s_mov_b32 s0, 0xf800000
	v_mul_f32_e32 v3, 0x4f800000, v1
	v_cmp_gt_f32_e32 vcc, s0, v1
	s_nop 1
	v_cndmask_b32_e32 v1, v1, v3, vcc
	v_sqrt_f32_e32 v3, v1
	s_nop 0
	v_add_u32_e32 v4, -1, v3
	v_add_u32_e32 v5, 1, v3
	v_fma_f32 v6, -v4, v3, v1
	v_fma_f32 v7, -v5, v3, v1
	v_cmp_ge_f32_e64 s[0:1], 0, v6
	s_nop 1
	v_cndmask_b32_e64 v3, v3, v4, s[0:1]
	v_cmp_lt_f32_e64 s[0:1], 0, v7
	s_nop 1
	v_cndmask_b32_e64 v3, v3, v5, s[0:1]
	v_mul_f32_e32 v4, 0x37800000, v3
	v_cndmask_b32_e32 v3, v3, v4, vcc
	v_cmp_class_f32_e32 vcc, v1, v236
	s_nop 1
	v_cndmask_b32_e32 v1, v3, v1, vcc
	v_div_scale_f32 v3, s[0:1], v1, v1, 1.0
	v_rcp_f32_e32 v4, v3
	v_div_scale_f32 v6, vcc, 1.0, v1, 1.0
	v_fma_f32 v7, -v3, v4, 1.0
	v_fmac_f32_e32 v4, v7, v4
	v_mul_f32_e32 v7, v6, v4
	v_fma_f32 v8, -v3, v7, v6
	v_fmac_f32_e32 v7, v8, v4
	v_fma_f32 v3, -v3, v7, v6
	v_div_fmas_f32 v3, v3, v4, v7
	v_div_fixup_f32 v1, v3, v1, 1.0
	v_cmp_lt_i32_e32 vcc, -1, v123
	s_and_saveexec_b64 s[6:7], vcc
	ds_write_b32 v22, v1 offset:6144
	s_mov_b64 exec, s[6:7]
	s_waitcnt vmcnt(4)
	v_add_f32_e32 v4, v89, v88
	v_add_f32_e32 v5, v90, v91
	v_add_f32_e32 v6, v93, v92
	v_add_f32_e32 v7, v94, v95
	v_add_f32_e32 v4, v4, v5
	v_add_f32_e32 v6, v6, v7
	v_add_f32_e32 v10, v96, v97
	v_add_f32_e32 v12, v98, v99
	v_add_f32_e32 v8, v10, v12
	v_add_f32_e32 v5, v100, v101
	v_add_f32_e32 v9, v102, v103
	v_add_f32_e32 v4, v4, v6
	v_add_f32_e32 v5, v5, v9
	v_add_f32_e32 v4, v4, v8
	v_add_f32_e32 v1, v4, v5
	v_fmamk_f32 v1, v1, 0x3a800000, v235
	s_mov_b32 s0, 0xf800000
	v_mul_f32_e32 v3, 0x4f800000, v1
	v_cmp_gt_f32_e32 vcc, s0, v1
	s_nop 1
	v_cndmask_b32_e32 v1, v1, v3, vcc
	v_sqrt_f32_e32 v3, v1
	s_nop 0
	v_add_u32_e32 v4, -1, v3
	v_add_u32_e32 v5, 1, v3
	v_fma_f32 v6, -v4, v3, v1
	v_fma_f32 v7, -v5, v3, v1
	v_cmp_ge_f32_e64 s[0:1], 0, v6
	s_nop 1
	v_cndmask_b32_e64 v3, v3, v4, s[0:1]
	v_cmp_lt_f32_e64 s[0:1], 0, v7
	s_nop 1
	v_cndmask_b32_e64 v3, v3, v5, s[0:1]
	v_mul_f32_e32 v4, 0x37800000, v3
	v_cndmask_b32_e32 v3, v3, v4, vcc
	v_cmp_class_f32_e32 vcc, v1, v236
	s_nop 1
	v_cndmask_b32_e32 v1, v3, v1, vcc
	v_div_scale_f32 v3, s[0:1], v1, v1, 1.0
	v_rcp_f32_e32 v4, v3
	v_div_scale_f32 v6, vcc, 1.0, v1, 1.0
	v_fma_f32 v7, -v3, v4, 1.0
	v_fmac_f32_e32 v4, v7, v4
	v_mul_f32_e32 v7, v6, v4
	v_fma_f32 v8, -v3, v7, v6
	v_fmac_f32_e32 v7, v8, v4
	v_fma_f32 v3, -v3, v7, v6
	v_div_fmas_f32 v3, v3, v4, v7
	v_div_fixup_f32 v1, v3, v1, 1.0
	v_cmp_lt_i32_e32 vcc, -1, v124
	s_and_saveexec_b64 s[6:7], vcc
	ds_write_b32 v22, v1 offset:8192
	s_mov_b64 exec, s[6:7]
	s_waitcnt vmcnt(0)
	v_add_f32_e32 v4, v105, v104
	v_add_f32_e32 v5, v106, v107
	v_add_f32_e32 v6, v109, v108
	v_add_f32_e32 v7, v110, v111
	v_add_f32_e32 v4, v4, v5
	v_add_f32_e32 v6, v6, v7
	v_add_f32_e32 v10, v112, v113
	v_add_f32_e32 v12, v114, v115
	v_add_f32_e32 v8, v10, v12
	v_add_f32_e32 v5, v116, v117
	v_add_f32_e32 v9, v118, v119
	v_add_f32_e32 v4, v4, v6
	v_add_f32_e32 v5, v5, v9
	v_add_f32_e32 v4, v4, v8
	v_add_f32_e32 v1, v4, v5
	v_fmamk_f32 v1, v1, 0x3a800000, v235
	s_mov_b32 s0, 0xf800000
	v_mul_f32_e32 v3, 0x4f800000, v1
	v_cmp_gt_f32_e32 vcc, s0, v1
	s_nop 1
	v_cndmask_b32_e32 v1, v1, v3, vcc
	v_sqrt_f32_e32 v3, v1
	s_nop 0
	v_add_u32_e32 v4, -1, v3
	v_add_u32_e32 v5, 1, v3
	v_fma_f32 v6, -v4, v3, v1
	v_fma_f32 v7, -v5, v3, v1
	v_cmp_ge_f32_e64 s[0:1], 0, v6
	s_nop 1
	v_cndmask_b32_e64 v3, v3, v4, s[0:1]
	v_cmp_lt_f32_e64 s[0:1], 0, v7
	s_nop 1
	v_cndmask_b32_e64 v3, v3, v5, s[0:1]
	v_mul_f32_e32 v4, 0x37800000, v3
	v_cndmask_b32_e32 v3, v3, v4, vcc
	v_cmp_class_f32_e32 vcc, v1, v236
	s_nop 1
	v_cndmask_b32_e32 v1, v3, v1, vcc
	v_div_scale_f32 v3, s[0:1], v1, v1, 1.0
	v_rcp_f32_e32 v4, v3
	v_div_scale_f32 v6, vcc, 1.0, v1, 1.0
	v_fma_f32 v7, -v3, v4, 1.0
	v_fmac_f32_e32 v4, v7, v4
	v_mul_f32_e32 v7, v6, v4
	v_fma_f32 v8, -v3, v7, v6
	v_fmac_f32_e32 v7, v8, v4
	v_fma_f32 v3, -v3, v7, v6
	v_div_fmas_f32 v3, v3, v4, v7
	v_div_fixup_f32 v1, v3, v1, 1.0
	v_cmp_lt_i32_e32 vcc, -1, v125
	s_and_saveexec_b64 s[6:7], vcc
	ds_write_b32 v22, v1 offset:10240
	s_mov_b64 exec, s[6:7]
